# ssd_out: C/B staging loads batched ahead of the barrier
# speedup vs baseline: 1.0201x; 1.0029x over previous
; DI f32x4 mmaT(bf16x8 a_m, bf16x8 b_n, f32x4 c) { return __builtin_amdgcn_mfma_f32_16x16x32_bf16(b_n, a_m, c, 0, 0, 0); }
; DI void ssd_out_unit(const Params& p, int layer, int hf, int bl, int c, unsigned char* shm, int tid, bool dry = false) {
;     ...
;   for (int g = 0; g < 2; ++g) {
;     __syncthreads();
; #pragma unroll
;     for (int it = 0; it < 4; ++it) {
;       const int idx = tid + it * NTHR, j = idx >> 4, ng = idx & 15;
;       *(uint4*)(sC + j * LD + ng * 8) = *(const uint4*)(xcb + (size_t)j * 1536 + 1280 + g * 128 + ng * 8);
;       *(uint4*)(sB + j * LD + ng * 8) = *(const uint4*)(xcb + (size_t)j * 1536 + 1024 + g * 128 + ng * 8);
;     }
;     __syncthreads();
;     f32x4 cbv[8];
;     {
;       bf16x8 ac[4];
; #pragma unroll
;       for (int ks = 0; ks < 4; ++ks) ac[ks] = ldf(sC, LD, 16 * wid, 32 * ks, fr, fq);
; #pragma unroll
;       for (int n = 0; n < 8; ++n) {
;         cbv[n] = (f32x4){0.f, 0.f, 0.f, 0.f};
;         if (n <= wid) {
; #pragma unroll
;           for (int ks = 0; ks < 4; ++ks) cbv[n] = mmaT(ac[ks], ldf(sB, LD, 16 * n, 32 * ks, fr, fq), cbv[n]);
;         }
;       }
.LBB0_503:
	s_lshl_b32 s2, s43, 8
	v_lshl_add_u64 v[4:5], v[90:91], 0, s[2:3]
	global_load_dwordx4 v[204:207], v[4:5], off offset:2560
	global_load_dwordx4 v[208:211], v[4:5], off offset:2048
	v_lshl_add_u64 v[4:5], v[94:95], 0, s[2:3]
	global_load_dwordx4 v[212:215], v[4:5], off offset:2560
	global_load_dwordx4 v[216:219], v[4:5], off offset:2048
	v_lshl_add_u64 v[4:5], v[98:99], 0, s[2:3]
	global_load_dwordx4 v[220:223], v[4:5], off offset:2560
	global_load_dwordx4 v[224:227], v[4:5], off offset:2048
	v_lshl_add_u64 v[4:5], v[102:103], 0, s[2:3]
	global_load_dwordx4 v[228:231], v[4:5], off offset:2560
	global_load_dwordx4 v[232:235], v[4:5], off offset:2048
	s_waitcnt lgkmcnt(0)
	s_barrier
	s_waitcnt vmcnt(0)
	ds_write_b128 v92, v[204:207]
	ds_write_b128 v93, v[208:211]
	ds_write_b128 v96, v[212:215]
	ds_write_b128 v97, v[216:219]
	ds_write_b128 v100, v[220:223]
	ds_write_b128 v101, v[224:227]
	ds_write_b128 v104, v[228:231]
	ds_write_b128 v105, v[232:235]
	v_add_u32_e32 v0, v121, v160
	s_waitcnt lgkmcnt(0)
	s_barrier
	ds_read_b128 v[44:47], v0
	ds_read_b128 v[40:43], v0 offset:64
	ds_read_b128 v[36:39], v0 offset:128
	ds_read_b128 v[32:35], v0 offset:192
	v_mov_b32_e32 v0, 0
	v_mov_b32_e32 v1, 0
	v_mov_b32_e32 v2, 0
	v_mov_b32_e32 v3, 0
	s_and_saveexec_b64 s[34:35], s[6:7]
	s_cbranch_execz .LBB0_505
	ds_read_b128 v[0:3], v133 offset:34816
	ds_read_b128 v[4:7], v133 offset:34880
	s_waitcnt lgkmcnt(1)
	v_mfma_f32_16x16x32_bf16 v[0:3], v[0:3], v[44:47], 0
	s_waitcnt lgkmcnt(0)
	v_mfma_f32_16x16x32_bf16 v[0:3], v[4:7], v[40:43], v[0:3]
	ds_read_b128 v[4:7], v133 offset:34944
	s_waitcnt lgkmcnt(0)
	v_mfma_f32_16x16x32_bf16 v[0:3], v[4:7], v[36:39], v[0:3]
	ds_read_b128 v[4:7], v133 offset:35008
	s_waitcnt lgkmcnt(0)
	v_mfma_f32_16x16x32_bf16 v[0:3], v[4:7], v[32:35], v[0:3]
